# attention unit epilogue: 8 dwordx2 stores per lane widened to 4 dwordx4 via v_permlane32_swap of neighbouring chunks
# speedup vs baseline: 1.0153x; 1.0036x over previous
.LBB0_259:
	v_div_scale_f32 v35, s[4:5], v34, v34, 1.0
	v_rcp_f32_e32 v36, v35
	v_div_scale_f32 v37, vcc, 1.0, v34, 1.0
	v_mov_b32_e32 v161, v193
	v_fma_f32 v38, -v35, v36, 1.0
	v_fmac_f32_e32 v36, v38, v36
	v_mul_f32_e32 v38, v37, v36
	v_fma_f32 v39, -v35, v38, v37
	v_fmac_f32_e32 v38, v39, v36
	v_fma_f32 v35, -v35, v38, v37
	v_div_fmas_f32 v35, v35, v36, v38
	v_div_fixup_f32 v34, v35, v34, 1.0
	v_pk_mul_f32 v[16:17], v[16:17], v[34:35] op_sel_hi:[1,0]
	v_pk_mul_f32 v[18:19], v[18:19], v[34:35] op_sel_hi:[1,0]
	v_pk_mul_f32 v[20:21], v[20:21], v[34:35] op_sel_hi:[1,0]
	v_pk_mul_f32 v[22:23], v[22:23], v[34:35] op_sel_hi:[1,0]
	v_pk_mul_f32 v[24:25], v[24:25], v[34:35] op_sel_hi:[1,0]
	v_pk_mul_f32 v[26:27], v[26:27], v[34:35] op_sel_hi:[1,0]
	v_pk_mul_f32 v[28:29], v[28:29], v[34:35] op_sel_hi:[1,0]
	v_pk_mul_f32 v[30:31], v[30:31], v[34:35] op_sel_hi:[1,0]
	v_pk_mul_f32 v[0:1], v[0:1], v[34:35] op_sel_hi:[1,0]
	v_pk_mul_f32 v[2:3], v[2:3], v[34:35] op_sel_hi:[1,0]
	v_pk_mul_f32 v[4:5], v[4:5], v[34:35] op_sel_hi:[1,0]
	v_pk_mul_f32 v[6:7], v[6:7], v[34:35] op_sel_hi:[1,0]
	v_pk_mul_f32 v[8:9], v[8:9], v[34:35] op_sel_hi:[1,0]
	v_pk_mul_f32 v[10:11], v[10:11], v[34:35] op_sel_hi:[1,0]
	v_pk_mul_f32 v[12:13], v[12:13], v[34:35] op_sel_hi:[1,0]
	v_pk_mul_f32 v[14:15], v[14:15], v[34:35] op_sel_hi:[1,0]
	v_lshl_add_u64 v[32:33], v[160:161], 1, v[32:33]
	v_lshl_add_u64 v[32:33], v[160:161], 1, v[32:33]
	v_cvt_pk_bf16_f32 v16, v16, v17
	v_cvt_pk_bf16_f32 v17, v18, v19
	v_cvt_pk_bf16_f32 v18, v20, v21
	v_cvt_pk_bf16_f32 v19, v22, v23
	v_cvt_pk_bf16_f32 v24, v24, v25
	v_cvt_pk_bf16_f32 v25, v26, v27
	v_cvt_pk_bf16_f32 v26, v28, v29
	v_cvt_pk_bf16_f32 v27, v30, v31
	v_cvt_pk_bf16_f32 v0, v0, v1
	v_cvt_pk_bf16_f32 v1, v2, v3
	v_cvt_pk_bf16_f32 v2, v4, v5
	v_cvt_pk_bf16_f32 v3, v6, v7
	v_cvt_pk_bf16_f32 v8, v8, v9
	v_cvt_pk_bf16_f32 v9, v10, v11
	v_cvt_pk_bf16_f32 v10, v12, v13
	v_cvt_pk_bf16_f32 v11, v14, v15
	s_nop 1
	v_permlane32_swap_b32_e32 v16, v18
	v_permlane32_swap_b32_e32 v17, v19
	v_permlane32_swap_b32_e32 v24, v26
	v_permlane32_swap_b32_e32 v25, v27
	v_permlane32_swap_b32_e32 v0, v2
	v_permlane32_swap_b32_e32 v1, v3
	v_permlane32_swap_b32_e32 v8, v10
	v_permlane32_swap_b32_e32 v9, v11
	global_store_dwordx4 v[32:33], v[16:19], off
	global_store_dwordx4 v[32:33], v[24:27], off offset:32
	global_store_dwordx4 v[32:33], v[0:3], off offset:64
	global_store_dwordx4 v[32:33], v[8:11], off offset:96
	s_xor_b32 s21, s21, 1
	s_and_saveexec_b64 s[4:5], s[42:43]
	s_cbranch_execz .LBB0_209
	s_lshl_b32 s6, s21, 2
	s_add_i32 s6, s6, 0
	s_add_i32 s6, s6, 0x15500
	v_mov_b32_e32 v0, s6
	s_branch .LBB0_209

.LBB0_310:
	v_div_scale_f32 v35, s[4:5], v34, v34, 1.0
	v_rcp_f32_e32 v36, v35
	v_div_scale_f32 v37, vcc, 1.0, v34, 1.0
	v_mov_b32_e32 v137, v193
	v_fma_f32 v38, -v35, v36, 1.0
	v_fmac_f32_e32 v36, v38, v36
	v_mul_f32_e32 v38, v37, v36
	v_fma_f32 v39, -v35, v38, v37
	v_fmac_f32_e32 v38, v39, v36
	v_fma_f32 v35, -v35, v38, v37
	v_div_fmas_f32 v35, v35, v36, v38
	v_div_fixup_f32 v34, v35, v34, 1.0
	v_pk_mul_f32 v[16:17], v[16:17], v[34:35] op_sel_hi:[1,0]
	v_pk_mul_f32 v[18:19], v[18:19], v[34:35] op_sel_hi:[1,0]
	v_pk_mul_f32 v[20:21], v[20:21], v[34:35] op_sel_hi:[1,0]
	v_pk_mul_f32 v[22:23], v[22:23], v[34:35] op_sel_hi:[1,0]
	v_pk_mul_f32 v[24:25], v[24:25], v[34:35] op_sel_hi:[1,0]
	v_pk_mul_f32 v[26:27], v[26:27], v[34:35] op_sel_hi:[1,0]
	v_pk_mul_f32 v[28:29], v[28:29], v[34:35] op_sel_hi:[1,0]
	v_pk_mul_f32 v[30:31], v[30:31], v[34:35] op_sel_hi:[1,0]
	v_pk_mul_f32 v[0:1], v[0:1], v[34:35] op_sel_hi:[1,0]
	v_pk_mul_f32 v[2:3], v[2:3], v[34:35] op_sel_hi:[1,0]
	v_pk_mul_f32 v[4:5], v[4:5], v[34:35] op_sel_hi:[1,0]
	v_pk_mul_f32 v[6:7], v[6:7], v[34:35] op_sel_hi:[1,0]
	v_pk_mul_f32 v[8:9], v[8:9], v[34:35] op_sel_hi:[1,0]
	v_pk_mul_f32 v[10:11], v[10:11], v[34:35] op_sel_hi:[1,0]
	v_pk_mul_f32 v[12:13], v[12:13], v[34:35] op_sel_hi:[1,0]
	v_pk_mul_f32 v[14:15], v[14:15], v[34:35] op_sel_hi:[1,0]
	v_lshl_add_u64 v[32:33], v[136:137], 1, v[32:33]
	v_lshl_add_u64 v[32:33], v[136:137], 1, v[32:33]
	v_cvt_pk_bf16_f32 v16, v16, v17
	v_cvt_pk_bf16_f32 v17, v18, v19
	v_cvt_pk_bf16_f32 v18, v20, v21
	v_cvt_pk_bf16_f32 v19, v22, v23
	v_cvt_pk_bf16_f32 v24, v24, v25
	v_cvt_pk_bf16_f32 v25, v26, v27
	v_cvt_pk_bf16_f32 v26, v28, v29
	v_cvt_pk_bf16_f32 v27, v30, v31
	v_cvt_pk_bf16_f32 v0, v0, v1
	v_cvt_pk_bf16_f32 v1, v2, v3
	v_cvt_pk_bf16_f32 v2, v4, v5
	v_cvt_pk_bf16_f32 v3, v6, v7
	v_cvt_pk_bf16_f32 v8, v8, v9
	v_cvt_pk_bf16_f32 v9, v10, v11
	v_cvt_pk_bf16_f32 v10, v12, v13
	v_cvt_pk_bf16_f32 v11, v14, v15
	s_nop 1
	v_permlane32_swap_b32_e32 v16, v18
	v_permlane32_swap_b32_e32 v17, v19
	v_permlane32_swap_b32_e32 v24, v26
	v_permlane32_swap_b32_e32 v25, v27
	v_permlane32_swap_b32_e32 v0, v2
	v_permlane32_swap_b32_e32 v1, v3
	v_permlane32_swap_b32_e32 v8, v10
	v_permlane32_swap_b32_e32 v9, v11
	global_store_dwordx4 v[32:33], v[16:19], off
	global_store_dwordx4 v[32:33], v[24:27], off offset:32
	global_store_dwordx4 v[32:33], v[0:3], off offset:64
	global_store_dwordx4 v[32:33], v[8:11], off offset:96
	s_xor_b32 s44, s44, 1
	s_and_saveexec_b64 s[4:5], s[40:41]
	s_cbranch_execz .LBB0_271
	s_lshl_b32 s8, s44, 2
	s_add_i32 s8, s8, 0
	s_add_i32 s8, s8, 0x15500
	v_mov_b32_e32 v0, s8
	s_branch .LBB0_271
